# v42: v34 with the s_setprio 0 that ends each 32-MFMA segment moved behind the segment-closing s_barrier (one instruction less between the last MFMA and the barrier the other wave half is waiting on),
# speedup vs baseline: 1.0011x; 1.0011x over previous
.LBB0_155:
	s_ashr_i32 s23, s22, 31
	s_lshl_b64 s[8:9], s[22:23], 19
	s_add_u32 s24, s30, s8
	s_addc_u32 s25, s31, s9
	s_and_b64 s[8:9], s[4:5], exec
	s_cselect_b32 s3, s25, s1
	s_cselect_b32 s23, s24, s0
	s_ashr_i32 s21, s20, 31
	s_lshl_b64 s[8:9], s[20:21], 19
	s_add_u32 s26, s34, s8
	s_addc_u32 s27, s35, s9
	s_and_b64 s[8:9], s[4:5], exec
	s_cselect_b32 s21, s27, s7
	s_cselect_b32 s28, s26, s6
	s_add_u32 s0, s0, 0x40080
	s_addc_u32 s1, s1, 0
	s_add_u32 s29, s6, 0x100
	s_addc_u32 s42, s7, 0
	s_mov_b32 s49, -2
	s_add_u32 s6, s0, 0xfffc0080
	s_addc_u32 s7, s1, -1
	s_add_i32 s50, 16, 0x10000
	s_cmp_eq_u32 s49, 12
	s_cselect_b32 s9, s3, s7
	s_cselect_b32 s8, s23, s6
	v_add_u32_e32 v151, s50, v176
	s_cselect_b32 s7, s21, s42
	s_cselect_b32 s6, s28, s29
	s_add_i32 s52, 16, 0x14000
	ds_read_b128 v[132:135], v151
	ds_read_b128 v[152:155], v151 offset:1024
	ds_read_b128 v[156:159], v151 offset:2048
	ds_read_b128 v[160:163], v151 offset:3072
	v_add_u32_e32 v151, s52, v176
	ds_read_b128 v[164:167], v151
	ds_read_b128 v[168:171], v151 offset:1024
	ds_read_b128 v[172:175], v151 offset:2048
	ds_read_b128 v[180:183], v151 offset:3072
	v_lshl_add_u64 v[216:217], s[0:1], 0, v[146:147]
	s_add_i32 m0, s37, 0xc000
	ds_read_b128 v[184:187], v178
	ds_read_b128 v[188:191], v178 offset:1024
	ds_read_b128 v[192:195], v178 offset:2048
	ds_read_b128 v[196:199], v178 offset:3072
	ds_read_b128 v[200:203], v178 offset:4096
	ds_read_b128 v[204:207], v178 offset:5120
	ds_read_b128 v[208:211], v178 offset:6144
	ds_read_b128 v[212:215], v178 offset:7168
	global_load_lds_dwordx4 v[216:217], off
	v_lshl_add_u64 v[216:217], s[0:1], 0, v[148:149]
	s_add_i32 m0, s37, 0xe000
	s_nop 0
	global_load_lds_dwordx4 v[216:217], off
	s_waitcnt vmcnt(8)
	s_waitcnt lgkmcnt(0)
	s_barrier
	s_setprio 1
	s_waitcnt lgkmcnt(0)
	v_mfma_f32_16x16x32_bf16 v[128:131], v[132:135], v[184:187], 0
	v_mfma_f32_16x16x32_bf16 v[124:127], v[156:159], v[184:187], 0
	v_mfma_f32_16x16x32_bf16 v[112:115], v[132:135], v[192:195], 0
	v_mfma_f32_16x16x32_bf16 v[108:111], v[156:159], v[192:195], 0
	v_mfma_f32_16x16x32_bf16 v[96:99], v[132:135], v[200:203], 0
	v_mfma_f32_16x16x32_bf16 v[92:95], v[156:159], v[200:203], 0
	v_mfma_f32_16x16x32_bf16 v[80:83], v[132:135], v[208:211], 0
	v_mfma_f32_16x16x32_bf16 v[76:79], v[156:159], v[208:211], 0
	v_mfma_f32_16x16x32_bf16 v[128:131], v[152:155], v[188:191], v[128:131]
	v_mfma_f32_16x16x32_bf16 v[124:127], v[160:163], v[188:191], v[124:127]
	v_mfma_f32_16x16x32_bf16 v[112:115], v[152:155], v[196:199], v[112:115]
	v_mfma_f32_16x16x32_bf16 v[108:111], v[160:163], v[196:199], v[108:111]
	v_mfma_f32_16x16x32_bf16 v[96:99], v[152:155], v[204:207], v[96:99]
	v_mfma_f32_16x16x32_bf16 v[92:95], v[160:163], v[204:207], v[92:95]
	v_mfma_f32_16x16x32_bf16 v[80:83], v[152:155], v[212:215], v[80:83]
	v_mfma_f32_16x16x32_bf16 v[76:79], v[160:163], v[212:215], v[76:79]
	s_setprio 0
	s_setprio 1
	v_mfma_f32_16x16x32_bf16 v[120:123], v[164:167], v[184:187], 0
	v_mfma_f32_16x16x32_bf16 v[116:119], v[172:175], v[184:187], 0
	v_mfma_f32_16x16x32_bf16 v[104:107], v[164:167], v[192:195], 0
	v_mfma_f32_16x16x32_bf16 v[100:103], v[172:175], v[192:195], 0
	v_mfma_f32_16x16x32_bf16 v[88:91], v[164:167], v[200:203], 0
	v_mfma_f32_16x16x32_bf16 v[84:87], v[172:175], v[200:203], 0
	v_mfma_f32_16x16x32_bf16 v[72:75], v[164:167], v[208:211], 0
	v_mfma_f32_16x16x32_bf16 v[68:71], v[172:175], v[208:211], 0
	v_mfma_f32_16x16x32_bf16 v[120:123], v[168:171], v[188:191], v[120:123]
	v_mfma_f32_16x16x32_bf16 v[116:119], v[180:183], v[188:191], v[116:119]
	v_mfma_f32_16x16x32_bf16 v[104:107], v[168:171], v[196:199], v[104:107]
	v_mfma_f32_16x16x32_bf16 v[100:103], v[180:183], v[196:199], v[100:103]
	v_mfma_f32_16x16x32_bf16 v[88:91], v[168:171], v[204:207], v[88:91]
	v_mfma_f32_16x16x32_bf16 v[84:87], v[180:183], v[204:207], v[84:87]
	v_mfma_f32_16x16x32_bf16 v[72:75], v[168:171], v[212:215], v[72:75]
	v_mfma_f32_16x16x32_bf16 v[68:71], v[180:183], v[212:215], v[68:71]
	s_barrier
	s_setprio 0
	s_add_i32 s50, s50, s36
	v_lshl_add_u64 v[216:217], s[6:7], 0, v[138:139]
	s_mov_b32 m0, s50
	ds_read_b128 v[184:187], v178 offset:16384
	ds_read_b128 v[188:191], v178 offset:17408
	ds_read_b128 v[192:195], v178 offset:18432
	ds_read_b128 v[196:199], v178 offset:19456
	ds_read_b128 v[200:203], v178 offset:20480
	ds_read_b128 v[204:207], v178 offset:21504
	ds_read_b128 v[208:211], v178 offset:22528
	ds_read_b128 v[212:215], v178 offset:23552
	global_load_lds_dwordx4 v[216:217], off
	s_add_i32 m0, s50, 0x2000
	s_add_u32 s50, s6, 0x40000
	v_lshl_add_u64 v[218:219], s[6:7], 0, v[0:1]
	s_addc_u32 s51, s7, 0
	s_add_i32 s52, s52, s36
	global_load_lds_dwordx4 v[218:219], off
	v_lshl_add_u64 v[220:221], s[50:51], 0, v[138:139]
	s_mov_b32 m0, s52
	v_lshl_add_u64 v[224:225], s[8:9], 0, v[136:137]
	global_load_lds_dwordx4 v[220:221], off
	v_lshl_add_u64 v[220:221], s[50:51], 0, v[0:1]
	s_add_i32 m0, s52, 0x2000
	s_nop 0
	global_load_lds_dwordx4 v[220:221], off
	v_lshl_add_u64 v[220:221], s[8:9], 0, v[140:141]
	s_waitcnt vmcnt(6)
	s_waitcnt lgkmcnt(0)
	s_barrier
	s_setprio 1
	s_waitcnt lgkmcnt(0)
	v_mfma_f32_16x16x32_bf16 v[64:67], v[132:135], v[184:187], 0
	v_mfma_f32_16x16x32_bf16 v[60:63], v[156:159], v[184:187], 0
	v_mfma_f32_16x16x32_bf16 v[48:51], v[132:135], v[192:195], 0
	v_mfma_f32_16x16x32_bf16 v[44:47], v[156:159], v[192:195], 0
	v_mfma_f32_16x16x32_bf16 v[32:35], v[132:135], v[200:203], 0
	v_mfma_f32_16x16x32_bf16 v[28:31], v[156:159], v[200:203], 0
	v_mfma_f32_16x16x32_bf16 v[16:19], v[132:135], v[208:211], 0
	v_mfma_f32_16x16x32_bf16 v[12:15], v[156:159], v[208:211], 0
	v_mfma_f32_16x16x32_bf16 v[64:67], v[152:155], v[188:191], v[64:67]
	v_mfma_f32_16x16x32_bf16 v[60:63], v[160:163], v[188:191], v[60:63]
	v_mfma_f32_16x16x32_bf16 v[48:51], v[152:155], v[196:199], v[48:51]
	v_mfma_f32_16x16x32_bf16 v[44:47], v[160:163], v[196:199], v[44:47]
	v_mfma_f32_16x16x32_bf16 v[32:35], v[152:155], v[204:207], v[32:35]
	v_mfma_f32_16x16x32_bf16 v[28:31], v[160:163], v[204:207], v[28:31]
	v_mfma_f32_16x16x32_bf16 v[16:19], v[152:155], v[212:215], v[16:19]
	v_mfma_f32_16x16x32_bf16 v[12:15], v[160:163], v[212:215], v[12:15]
	s_setprio 0
	s_setprio 1
	v_mfma_f32_16x16x32_bf16 v[56:59], v[164:167], v[184:187], 0
	v_mfma_f32_16x16x32_bf16 v[52:55], v[172:175], v[184:187], 0
	v_mfma_f32_16x16x32_bf16 v[40:43], v[164:167], v[192:195], 0
	v_mfma_f32_16x16x32_bf16 v[36:39], v[172:175], v[192:195], 0
	v_mfma_f32_16x16x32_bf16 v[24:27], v[164:167], v[200:203], 0
	v_mfma_f32_16x16x32_bf16 v[20:23], v[172:175], v[200:203], 0
	v_mfma_f32_16x16x32_bf16 v[8:11], v[164:167], v[208:211], 0
	v_mfma_f32_16x16x32_bf16 v[4:7], v[172:175], v[208:211], 0
	v_mfma_f32_16x16x32_bf16 v[56:59], v[168:171], v[188:191], v[56:59]
	v_mfma_f32_16x16x32_bf16 v[52:55], v[180:183], v[188:191], v[52:55]
	v_mfma_f32_16x16x32_bf16 v[40:43], v[168:171], v[196:199], v[40:43]
	v_mfma_f32_16x16x32_bf16 v[36:39], v[180:183], v[196:199], v[36:39]
	v_mfma_f32_16x16x32_bf16 v[24:27], v[168:171], v[204:207], v[24:27]
	v_mfma_f32_16x16x32_bf16 v[20:23], v[180:183], v[204:207], v[20:23]
	v_mfma_f32_16x16x32_bf16 v[8:11], v[168:171], v[212:215], v[8:11]
	v_mfma_f32_16x16x32_bf16 v[4:7], v[180:183], v[212:215], v[4:7]
	s_barrier
	s_setprio 0
	s_branch .Lb1_ph3
.LBB0_156:
	s_add_u32 s6, s0, 0xfffc0080
	s_addc_u32 s7, s1, -1
	s_add_i32 s50, 16, 0x10000
	s_cmp_eq_u32 s49, 12
	s_cselect_b32 s9, s3, s7
	s_cselect_b32 s8, s23, s6
	v_add_u32_e32 v151, s50, v176
	s_cselect_b32 s7, s21, s42
	s_cselect_b32 s6, s28, s29
	s_add_i32 s52, 16, 0x14000
	ds_read_b128 v[132:135], v151
	ds_read_b128 v[152:155], v151 offset:1024
	ds_read_b128 v[156:159], v151 offset:2048
	ds_read_b128 v[160:163], v151 offset:3072
	v_add_u32_e32 v151, s52, v176
	ds_read_b128 v[164:167], v151
	ds_read_b128 v[168:171], v151 offset:1024
	ds_read_b128 v[172:175], v151 offset:2048
	ds_read_b128 v[180:183], v151 offset:3072
	v_lshl_add_u64 v[216:217], s[0:1], 0, v[146:147]
	s_add_i32 m0, s37, 0xc000
	ds_read_b128 v[184:187], v178
	ds_read_b128 v[188:191], v178 offset:1024
	ds_read_b128 v[192:195], v178 offset:2048
	ds_read_b128 v[196:199], v178 offset:3072
	ds_read_b128 v[200:203], v178 offset:4096
	ds_read_b128 v[204:207], v178 offset:5120
	ds_read_b128 v[208:211], v178 offset:6144
	ds_read_b128 v[212:215], v178 offset:7168
	global_load_lds_dwordx4 v[216:217], off
	v_lshl_add_u64 v[216:217], s[0:1], 0, v[148:149]
	s_add_i32 m0, s37, 0xe000
	s_nop 0
	global_load_lds_dwordx4 v[216:217], off
	s_waitcnt vmcnt(8)
	s_waitcnt lgkmcnt(0)
	s_barrier
	s_setprio 1
	s_waitcnt lgkmcnt(0)
	v_mfma_f32_16x16x32_bf16 v[128:131], v[132:135], v[184:187], v[128:131]
	v_mfma_f32_16x16x32_bf16 v[124:127], v[156:159], v[184:187], v[124:127]
	v_mfma_f32_16x16x32_bf16 v[112:115], v[132:135], v[192:195], v[112:115]
	v_mfma_f32_16x16x32_bf16 v[108:111], v[156:159], v[192:195], v[108:111]
	v_mfma_f32_16x16x32_bf16 v[96:99], v[132:135], v[200:203], v[96:99]
	v_mfma_f32_16x16x32_bf16 v[92:95], v[156:159], v[200:203], v[92:95]
	v_mfma_f32_16x16x32_bf16 v[80:83], v[132:135], v[208:211], v[80:83]
	v_mfma_f32_16x16x32_bf16 v[76:79], v[156:159], v[208:211], v[76:79]
	v_mfma_f32_16x16x32_bf16 v[128:131], v[152:155], v[188:191], v[128:131]
	v_mfma_f32_16x16x32_bf16 v[124:127], v[160:163], v[188:191], v[124:127]
	v_mfma_f32_16x16x32_bf16 v[112:115], v[152:155], v[196:199], v[112:115]
	v_mfma_f32_16x16x32_bf16 v[108:111], v[160:163], v[196:199], v[108:111]
	v_mfma_f32_16x16x32_bf16 v[96:99], v[152:155], v[204:207], v[96:99]
	v_mfma_f32_16x16x32_bf16 v[92:95], v[160:163], v[204:207], v[92:95]
	v_mfma_f32_16x16x32_bf16 v[80:83], v[152:155], v[212:215], v[80:83]
	v_mfma_f32_16x16x32_bf16 v[76:79], v[160:163], v[212:215], v[76:79]
	s_setprio 0
	s_setprio 1
	v_mfma_f32_16x16x32_bf16 v[120:123], v[164:167], v[184:187], v[120:123]
	v_mfma_f32_16x16x32_bf16 v[116:119], v[172:175], v[184:187], v[116:119]
	v_mfma_f32_16x16x32_bf16 v[104:107], v[164:167], v[192:195], v[104:107]
	v_mfma_f32_16x16x32_bf16 v[100:103], v[172:175], v[192:195], v[100:103]
	v_mfma_f32_16x16x32_bf16 v[88:91], v[164:167], v[200:203], v[88:91]
	v_mfma_f32_16x16x32_bf16 v[84:87], v[172:175], v[200:203], v[84:87]
	v_mfma_f32_16x16x32_bf16 v[72:75], v[164:167], v[208:211], v[72:75]
	v_mfma_f32_16x16x32_bf16 v[68:71], v[172:175], v[208:211], v[68:71]
	v_mfma_f32_16x16x32_bf16 v[120:123], v[168:171], v[188:191], v[120:123]
	v_mfma_f32_16x16x32_bf16 v[116:119], v[180:183], v[188:191], v[116:119]
	v_mfma_f32_16x16x32_bf16 v[104:107], v[168:171], v[196:199], v[104:107]
	v_mfma_f32_16x16x32_bf16 v[100:103], v[180:183], v[196:199], v[100:103]
	v_mfma_f32_16x16x32_bf16 v[88:91], v[168:171], v[204:207], v[88:91]
	v_mfma_f32_16x16x32_bf16 v[84:87], v[180:183], v[204:207], v[84:87]
	v_mfma_f32_16x16x32_bf16 v[72:75], v[168:171], v[212:215], v[72:75]
	v_mfma_f32_16x16x32_bf16 v[68:71], v[180:183], v[212:215], v[68:71]
	s_barrier
	s_setprio 0
	s_add_i32 s50, s50, s36
	v_lshl_add_u64 v[216:217], s[6:7], 0, v[138:139]
	s_mov_b32 m0, s50
	ds_read_b128 v[184:187], v178 offset:16384
	ds_read_b128 v[188:191], v178 offset:17408
	ds_read_b128 v[192:195], v178 offset:18432
	ds_read_b128 v[196:199], v178 offset:19456
	ds_read_b128 v[200:203], v178 offset:20480
	ds_read_b128 v[204:207], v178 offset:21504
	ds_read_b128 v[208:211], v178 offset:22528
	ds_read_b128 v[212:215], v178 offset:23552
	global_load_lds_dwordx4 v[216:217], off
	s_add_i32 m0, s50, 0x2000
	s_add_u32 s50, s6, 0x40000
	v_lshl_add_u64 v[218:219], s[6:7], 0, v[0:1]
	s_addc_u32 s51, s7, 0
	s_add_i32 s52, s52, s36
	global_load_lds_dwordx4 v[218:219], off
	v_lshl_add_u64 v[220:221], s[50:51], 0, v[138:139]
	s_mov_b32 m0, s52
	v_lshl_add_u64 v[224:225], s[8:9], 0, v[136:137]
	global_load_lds_dwordx4 v[220:221], off
	v_lshl_add_u64 v[220:221], s[50:51], 0, v[0:1]
	s_add_i32 m0, s52, 0x2000
	s_nop 0
	global_load_lds_dwordx4 v[220:221], off
	v_lshl_add_u64 v[220:221], s[8:9], 0, v[140:141]
	s_waitcnt vmcnt(6)
	s_waitcnt lgkmcnt(0)
	s_barrier
	s_setprio 1
	s_waitcnt lgkmcnt(0)
	v_mfma_f32_16x16x32_bf16 v[64:67], v[132:135], v[184:187], v[64:67]
	v_mfma_f32_16x16x32_bf16 v[60:63], v[156:159], v[184:187], v[60:63]
	v_mfma_f32_16x16x32_bf16 v[48:51], v[132:135], v[192:195], v[48:51]
	v_mfma_f32_16x16x32_bf16 v[44:47], v[156:159], v[192:195], v[44:47]
	v_mfma_f32_16x16x32_bf16 v[32:35], v[132:135], v[200:203], v[32:35]
	v_mfma_f32_16x16x32_bf16 v[28:31], v[156:159], v[200:203], v[28:31]
	v_mfma_f32_16x16x32_bf16 v[16:19], v[132:135], v[208:211], v[16:19]
	v_mfma_f32_16x16x32_bf16 v[12:15], v[156:159], v[208:211], v[12:15]
	v_mfma_f32_16x16x32_bf16 v[64:67], v[152:155], v[188:191], v[64:67]
	v_mfma_f32_16x16x32_bf16 v[60:63], v[160:163], v[188:191], v[60:63]
	v_mfma_f32_16x16x32_bf16 v[48:51], v[152:155], v[196:199], v[48:51]
	v_mfma_f32_16x16x32_bf16 v[44:47], v[160:163], v[196:199], v[44:47]
	v_mfma_f32_16x16x32_bf16 v[32:35], v[152:155], v[204:207], v[32:35]
	v_mfma_f32_16x16x32_bf16 v[28:31], v[160:163], v[204:207], v[28:31]
	v_mfma_f32_16x16x32_bf16 v[16:19], v[152:155], v[212:215], v[16:19]
	v_mfma_f32_16x16x32_bf16 v[12:15], v[160:163], v[212:215], v[12:15]
	s_setprio 0
	s_setprio 1
	v_mfma_f32_16x16x32_bf16 v[56:59], v[164:167], v[184:187], v[56:59]
	v_mfma_f32_16x16x32_bf16 v[52:55], v[172:175], v[184:187], v[52:55]
	v_mfma_f32_16x16x32_bf16 v[40:43], v[164:167], v[192:195], v[40:43]
	v_mfma_f32_16x16x32_bf16 v[36:39], v[172:175], v[192:195], v[36:39]
	v_mfma_f32_16x16x32_bf16 v[24:27], v[164:167], v[200:203], v[24:27]
	v_mfma_f32_16x16x32_bf16 v[20:23], v[172:175], v[200:203], v[20:23]
	v_mfma_f32_16x16x32_bf16 v[8:11], v[164:167], v[208:211], v[8:11]
	v_mfma_f32_16x16x32_bf16 v[4:7], v[172:175], v[208:211], v[4:7]
	v_mfma_f32_16x16x32_bf16 v[56:59], v[168:171], v[188:191], v[56:59]
	v_mfma_f32_16x16x32_bf16 v[52:55], v[180:183], v[188:191], v[52:55]
	v_mfma_f32_16x16x32_bf16 v[40:43], v[168:171], v[196:199], v[40:43]
	v_mfma_f32_16x16x32_bf16 v[36:39], v[180:183], v[196:199], v[36:39]
	v_mfma_f32_16x16x32_bf16 v[24:27], v[168:171], v[204:207], v[24:27]
	v_mfma_f32_16x16x32_bf16 v[20:23], v[180:183], v[204:207], v[20:23]
	v_mfma_f32_16x16x32_bf16 v[8:11], v[168:171], v[212:215], v[8:11]
	v_mfma_f32_16x16x32_bf16 v[4:7], v[180:183], v[212:215], v[4:7]
	s_barrier
	s_setprio 0

.Lb1pf_skip:
	s_waitcnt lgkmcnt(0)
	s_barrier
	s_setprio 1
	s_waitcnt lgkmcnt(0)
	v_mfma_f32_16x16x32_bf16 v[128:131], v[132:135], v[184:187], v[128:131]
	v_mfma_f32_16x16x32_bf16 v[124:127], v[156:159], v[184:187], v[124:127]
	v_mfma_f32_16x16x32_bf16 v[112:115], v[132:135], v[192:195], v[112:115]
	v_mfma_f32_16x16x32_bf16 v[108:111], v[156:159], v[192:195], v[108:111]
	v_mfma_f32_16x16x32_bf16 v[96:99], v[132:135], v[200:203], v[96:99]
	v_mfma_f32_16x16x32_bf16 v[92:95], v[156:159], v[200:203], v[92:95]
	v_mfma_f32_16x16x32_bf16 v[80:83], v[132:135], v[208:211], v[80:83]
	v_mfma_f32_16x16x32_bf16 v[76:79], v[156:159], v[208:211], v[76:79]
	v_mfma_f32_16x16x32_bf16 v[128:131], v[152:155], v[188:191], v[128:131]
	v_mfma_f32_16x16x32_bf16 v[124:127], v[160:163], v[188:191], v[124:127]
	v_mfma_f32_16x16x32_bf16 v[112:115], v[152:155], v[196:199], v[112:115]
	v_mfma_f32_16x16x32_bf16 v[108:111], v[160:163], v[196:199], v[108:111]
	v_mfma_f32_16x16x32_bf16 v[96:99], v[152:155], v[204:207], v[96:99]
	v_mfma_f32_16x16x32_bf16 v[92:95], v[160:163], v[204:207], v[92:95]
	v_mfma_f32_16x16x32_bf16 v[80:83], v[152:155], v[212:215], v[80:83]
	v_mfma_f32_16x16x32_bf16 v[76:79], v[160:163], v[212:215], v[76:79]
	s_setprio 0
	s_setprio 1
	v_mfma_f32_16x16x32_bf16 v[120:123], v[164:167], v[184:187], v[120:123]
	v_mfma_f32_16x16x32_bf16 v[116:119], v[172:175], v[184:187], v[116:119]
	v_mfma_f32_16x16x32_bf16 v[104:107], v[164:167], v[192:195], v[104:107]
	v_mfma_f32_16x16x32_bf16 v[100:103], v[172:175], v[192:195], v[100:103]
	v_mfma_f32_16x16x32_bf16 v[88:91], v[164:167], v[200:203], v[88:91]
	v_mfma_f32_16x16x32_bf16 v[84:87], v[172:175], v[200:203], v[84:87]
	v_mfma_f32_16x16x32_bf16 v[72:75], v[164:167], v[208:211], v[72:75]
	v_mfma_f32_16x16x32_bf16 v[68:71], v[172:175], v[208:211], v[68:71]
	v_mfma_f32_16x16x32_bf16 v[120:123], v[168:171], v[188:191], v[120:123]
	v_mfma_f32_16x16x32_bf16 v[116:119], v[180:183], v[188:191], v[116:119]
	v_mfma_f32_16x16x32_bf16 v[104:107], v[168:171], v[196:199], v[104:107]
	v_mfma_f32_16x16x32_bf16 v[100:103], v[180:183], v[196:199], v[100:103]
	v_mfma_f32_16x16x32_bf16 v[88:91], v[168:171], v[204:207], v[88:91]
	v_mfma_f32_16x16x32_bf16 v[84:87], v[180:183], v[204:207], v[84:87]
	v_mfma_f32_16x16x32_bf16 v[72:75], v[168:171], v[212:215], v[72:75]
	v_mfma_f32_16x16x32_bf16 v[68:71], v[180:183], v[212:215], v[68:71]
	s_barrier
	s_setprio 0
	s_add_i32 s8, s50, s36
	v_lshl_add_u64 v[216:217], v[216:217], 0, s[84:85]
	s_mov_b32 m0, s8
	ds_read_b128 v[184:187], v178 offset:49152
	ds_read_b128 v[188:191], v178 offset:50176
	ds_read_b128 v[192:195], v178 offset:51200
	ds_read_b128 v[196:199], v178 offset:52224
	ds_read_b128 v[200:203], v178 offset:53248
	ds_read_b128 v[204:207], v178 offset:54272
	ds_read_b128 v[208:211], v178 offset:55296
	ds_read_b128 v[212:215], v178 offset:56320
	global_load_lds_dwordx4 v[216:217], off
	s_add_i32 m0, s8, 0x2000
	s_add_u32 s6, s6, 0x40080
	v_lshl_add_u64 v[216:217], v[218:219], 0, s[84:85]
	s_addc_u32 s7, s7, 0
	s_add_i32 s8, s51, s36
	global_load_lds_dwordx4 v[216:217], off
	v_lshl_add_u64 v[216:217], s[6:7], 0, v[138:139]
	s_mov_b32 m0, s8
	s_nop 0
	global_load_lds_dwordx4 v[216:217], off
	v_lshl_add_u64 v[216:217], s[6:7], 0, v[0:1]
	s_add_i32 m0, s8, 0x2000
	s_nop 0
	global_load_lds_dwordx4 v[216:217], off
	v_lshl_add_u64 v[216:217], v[220:221], 0, s[84:85]
	s_mov_b32 m0, s44
	s_nop 0
	global_load_lds_dwordx4 v[216:217], off
	v_lshl_add_u64 v[216:217], v[224:225], 0, s[84:85]
	s_mov_b32 m0, s45
	s_nop 0
	global_load_lds_dwordx4 v[216:217], off
	s_cmp_eq_u32 s49, 12
	s_cbranch_scc1 .Lb1w4_last
	s_waitcnt vmcnt(8)
	s_branch .Lb1w4_j

.Lb1w4_j:
	s_waitcnt lgkmcnt(0)
	s_barrier
	s_setprio 1
	s_waitcnt lgkmcnt(0)
	v_mfma_f32_16x16x32_bf16 v[64:67], v[132:135], v[184:187], v[64:67]
	v_mfma_f32_16x16x32_bf16 v[60:63], v[156:159], v[184:187], v[60:63]
	v_mfma_f32_16x16x32_bf16 v[48:51], v[132:135], v[192:195], v[48:51]
	v_mfma_f32_16x16x32_bf16 v[44:47], v[156:159], v[192:195], v[44:47]
	v_mfma_f32_16x16x32_bf16 v[32:35], v[132:135], v[200:203], v[32:35]
	v_mfma_f32_16x16x32_bf16 v[28:31], v[156:159], v[200:203], v[28:31]
	v_mfma_f32_16x16x32_bf16 v[16:19], v[132:135], v[208:211], v[16:19]
	v_mfma_f32_16x16x32_bf16 v[12:15], v[156:159], v[208:211], v[12:15]
	v_mfma_f32_16x16x32_bf16 v[64:67], v[152:155], v[188:191], v[64:67]
	v_mfma_f32_16x16x32_bf16 v[60:63], v[160:163], v[188:191], v[60:63]
	v_mfma_f32_16x16x32_bf16 v[48:51], v[152:155], v[196:199], v[48:51]
	v_mfma_f32_16x16x32_bf16 v[44:47], v[160:163], v[196:199], v[44:47]
	v_mfma_f32_16x16x32_bf16 v[32:35], v[152:155], v[204:207], v[32:35]
	v_mfma_f32_16x16x32_bf16 v[28:31], v[160:163], v[204:207], v[28:31]
	v_mfma_f32_16x16x32_bf16 v[16:19], v[152:155], v[212:215], v[16:19]
	v_mfma_f32_16x16x32_bf16 v[12:15], v[160:163], v[212:215], v[12:15]
	s_setprio 0
	s_setprio 1
	v_mfma_f32_16x16x32_bf16 v[56:59], v[164:167], v[184:187], v[56:59]
	v_mfma_f32_16x16x32_bf16 v[52:55], v[172:175], v[184:187], v[52:55]
	v_mfma_f32_16x16x32_bf16 v[40:43], v[164:167], v[192:195], v[40:43]
	v_mfma_f32_16x16x32_bf16 v[36:39], v[172:175], v[192:195], v[36:39]
	v_mfma_f32_16x16x32_bf16 v[24:27], v[164:167], v[200:203], v[24:27]
	v_mfma_f32_16x16x32_bf16 v[20:23], v[172:175], v[200:203], v[20:23]
	v_mfma_f32_16x16x32_bf16 v[8:11], v[164:167], v[208:211], v[8:11]
	v_mfma_f32_16x16x32_bf16 v[4:7], v[172:175], v[208:211], v[4:7]
	v_mfma_f32_16x16x32_bf16 v[56:59], v[168:171], v[188:191], v[56:59]
	v_mfma_f32_16x16x32_bf16 v[52:55], v[180:183], v[188:191], v[52:55]
	v_mfma_f32_16x16x32_bf16 v[40:43], v[168:171], v[196:199], v[40:43]
	v_mfma_f32_16x16x32_bf16 v[36:39], v[180:183], v[196:199], v[36:39]
	v_mfma_f32_16x16x32_bf16 v[24:27], v[168:171], v[204:207], v[24:27]
	v_mfma_f32_16x16x32_bf16 v[20:23], v[180:183], v[204:207], v[20:23]
	v_mfma_f32_16x16x32_bf16 v[8:11], v[168:171], v[212:215], v[8:11]
	v_mfma_f32_16x16x32_bf16 v[4:7], v[180:183], v[212:215], v[4:7]
	s_barrier
	s_setprio 0
	s_add_i32 s49, s49, 2
	s_add_u32 s0, s0, 0x100
	s_addc_u32 s1, s1, 0
	s_add_u32 s29, s29, 0x100
	s_addc_u32 s42, s42, 0
	s_cmp_gt_u32 s49, 13
	s_cbranch_scc0 .LBB0_156
	s_and_b64 vcc, exec, s[18:19]
	s_cbranch_vccz .LBB0_159
	s_barrier

.LBB0_445:
	s_ashr_i32 s23, s22, 31
	s_lshl_b64 s[24:25], s[22:23], 19
	s_add_u32 s24, s34, s24
	s_addc_u32 s25, s35, s25
	s_and_b64 s[26:27], s[6:7], exec
	s_cselect_b32 s3, s25, s1
	s_cselect_b32 s23, s24, s0
	s_ashr_i32 s21, s20, 31
	s_lshl_b64 s[26:27], s[20:21], 19
	s_add_u32 s26, s36, s26
	s_addc_u32 s27, s37, s27
	s_and_b64 s[30:31], s[6:7], exec
	s_cselect_b32 s21, s27, s29
	s_cselect_b32 s48, s26, s28
	s_add_u32 s0, s0, 0x40080
	s_addc_u32 s1, s1, 0
	s_add_u32 s49, s28, 0x100
	s_addc_u32 s50, s29, 0
	s_mov_b32 s51, -2
	s_waitcnt vmcnt(0)
	s_add_u32 s28, s0, 0xfffc0080
	s_addc_u32 s29, s1, -1
	s_add_i32 s52, 16, 0x10000
	s_cmp_eq_u32 s51, 12
	s_cselect_b32 s31, s3, s29
	s_cselect_b32 s30, s23, s28
	v_add_u32_e32 v3, s52, v175
	s_cselect_b32 s29, s21, s50
	s_cselect_b32 s28, s48, s49
	s_add_i32 s54, 16, 0x14000
	ds_read_b128 v[142:145], v3
	ds_read_b128 v[146:149], v3 offset:1024
	ds_read_b128 v[150:153], v3 offset:2048
	ds_read_b128 v[154:157], v3 offset:3072
	v_add_u32_e32 v3, s54, v175
	ds_read_b128 v[158:161], v3
	ds_read_b128 v[162:165], v3 offset:1024
	ds_read_b128 v[166:169], v3 offset:2048
	ds_read_b128 v[170:173], v3 offset:3072
	v_lshl_add_u64 v[210:211], s[0:1], 0, v[138:139]
	s_add_i32 m0, s39, 0xc000
	ds_read_b128 v[178:181], v177
	ds_read_b128 v[182:185], v177 offset:1024
	ds_read_b128 v[186:189], v177 offset:2048
	ds_read_b128 v[190:193], v177 offset:3072
	ds_read_b128 v[194:197], v177 offset:4096
	ds_read_b128 v[198:201], v177 offset:5120
	ds_read_b128 v[202:205], v177 offset:6144
	ds_read_b128 v[206:209], v177 offset:7168
	global_load_lds_dwordx4 v[210:211], off
	v_lshl_add_u64 v[210:211], s[0:1], 0, v[140:141]
	s_add_i32 m0, s39, 0xe000
	s_nop 0
	global_load_lds_dwordx4 v[210:211], off
	s_waitcnt vmcnt(8)
	s_waitcnt lgkmcnt(0)
	s_barrier
	s_setprio 1
	s_waitcnt lgkmcnt(0)
	v_mfma_f32_16x16x32_bf16 v[128:131], v[142:145], v[178:181], 0
	v_mfma_f32_16x16x32_bf16 v[120:123], v[150:153], v[178:181], 0
	v_mfma_f32_16x16x32_bf16 v[112:115], v[142:145], v[186:189], 0
	v_mfma_f32_16x16x32_bf16 v[104:107], v[150:153], v[186:189], 0
	v_mfma_f32_16x16x32_bf16 v[96:99], v[142:145], v[194:197], 0
	v_mfma_f32_16x16x32_bf16 v[88:91], v[150:153], v[194:197], 0
	v_mfma_f32_16x16x32_bf16 v[80:83], v[142:145], v[202:205], 0
	v_mfma_f32_16x16x32_bf16 v[72:75], v[150:153], v[202:205], 0
	v_mfma_f32_16x16x32_bf16 v[128:131], v[146:149], v[182:185], v[128:131]
	v_mfma_f32_16x16x32_bf16 v[120:123], v[154:157], v[182:185], v[120:123]
	v_mfma_f32_16x16x32_bf16 v[112:115], v[146:149], v[190:193], v[112:115]
	v_mfma_f32_16x16x32_bf16 v[104:107], v[154:157], v[190:193], v[104:107]
	v_mfma_f32_16x16x32_bf16 v[96:99], v[146:149], v[198:201], v[96:99]
	v_mfma_f32_16x16x32_bf16 v[88:91], v[154:157], v[198:201], v[88:91]
	v_mfma_f32_16x16x32_bf16 v[80:83], v[146:149], v[206:209], v[80:83]
	v_mfma_f32_16x16x32_bf16 v[72:75], v[154:157], v[206:209], v[72:75]
	s_setprio 0
	s_setprio 1
	v_mfma_f32_16x16x32_bf16 v[124:127], v[158:161], v[178:181], 0
	v_mfma_f32_16x16x32_bf16 v[116:119], v[166:169], v[178:181], 0
	v_mfma_f32_16x16x32_bf16 v[108:111], v[158:161], v[186:189], 0
	v_mfma_f32_16x16x32_bf16 v[100:103], v[166:169], v[186:189], 0
	v_mfma_f32_16x16x32_bf16 v[92:95], v[158:161], v[194:197], 0
	v_mfma_f32_16x16x32_bf16 v[84:87], v[166:169], v[194:197], 0
	v_mfma_f32_16x16x32_bf16 v[76:79], v[158:161], v[202:205], 0
	v_mfma_f32_16x16x32_bf16 v[68:71], v[166:169], v[202:205], 0
	v_mfma_f32_16x16x32_bf16 v[124:127], v[162:165], v[182:185], v[124:127]
	v_mfma_f32_16x16x32_bf16 v[116:119], v[170:173], v[182:185], v[116:119]
	v_mfma_f32_16x16x32_bf16 v[108:111], v[162:165], v[190:193], v[108:111]
	v_mfma_f32_16x16x32_bf16 v[100:103], v[170:173], v[190:193], v[100:103]
	v_mfma_f32_16x16x32_bf16 v[92:95], v[162:165], v[198:201], v[92:95]
	v_mfma_f32_16x16x32_bf16 v[84:87], v[170:173], v[198:201], v[84:87]
	v_mfma_f32_16x16x32_bf16 v[76:79], v[162:165], v[206:209], v[76:79]
	v_mfma_f32_16x16x32_bf16 v[68:71], v[170:173], v[206:209], v[68:71]
	s_barrier
	s_setprio 0
	s_add_i32 s52, s52, s38
	v_lshl_add_u64 v[210:211], s[28:29], 0, v[134:135]
	s_mov_b32 m0, s52
	ds_read_b128 v[178:181], v177 offset:16384
	ds_read_b128 v[182:185], v177 offset:17408
	ds_read_b128 v[186:189], v177 offset:18432
	ds_read_b128 v[190:193], v177 offset:19456
	ds_read_b128 v[194:197], v177 offset:20480
	ds_read_b128 v[198:201], v177 offset:21504
	ds_read_b128 v[202:205], v177 offset:22528
	ds_read_b128 v[206:209], v177 offset:23552
	global_load_lds_dwordx4 v[210:211], off
	s_add_i32 m0, s52, 0x2000
	s_add_u32 s52, s28, 0x40000
	v_lshl_add_u64 v[212:213], s[28:29], 0, v[0:1]
	s_addc_u32 s53, s29, 0
	s_add_i32 s54, s54, s38
	global_load_lds_dwordx4 v[212:213], off
	v_lshl_add_u64 v[214:215], s[52:53], 0, v[134:135]
	s_mov_b32 m0, s54
	v_lshl_add_u64 v[216:217], s[30:31], 0, v[132:133]
	global_load_lds_dwordx4 v[214:215], off
	v_lshl_add_u64 v[214:215], s[52:53], 0, v[0:1]
	s_add_i32 m0, s54, 0x2000
	s_nop 0
	global_load_lds_dwordx4 v[214:215], off
	v_lshl_add_u64 v[214:215], s[30:31], 0, v[136:137]
	s_waitcnt vmcnt(6)
	s_waitcnt lgkmcnt(0)
	s_barrier
	s_setprio 1
	s_waitcnt lgkmcnt(0)
	v_mfma_f32_16x16x32_bf16 v[64:67], v[142:145], v[178:181], 0
	v_mfma_f32_16x16x32_bf16 v[56:59], v[150:153], v[178:181], 0
	v_mfma_f32_16x16x32_bf16 v[48:51], v[142:145], v[186:189], 0
	v_mfma_f32_16x16x32_bf16 v[40:43], v[150:153], v[186:189], 0
	v_mfma_f32_16x16x32_bf16 v[32:35], v[142:145], v[194:197], 0
	v_mfma_f32_16x16x32_bf16 v[24:27], v[150:153], v[194:197], 0
	v_mfma_f32_16x16x32_bf16 v[16:19], v[142:145], v[202:205], 0
	v_mfma_f32_16x16x32_bf16 v[8:11], v[150:153], v[202:205], 0
	v_mfma_f32_16x16x32_bf16 v[64:67], v[146:149], v[182:185], v[64:67]
	v_mfma_f32_16x16x32_bf16 v[56:59], v[154:157], v[182:185], v[56:59]
	v_mfma_f32_16x16x32_bf16 v[48:51], v[146:149], v[190:193], v[48:51]
	v_mfma_f32_16x16x32_bf16 v[40:43], v[154:157], v[190:193], v[40:43]
	v_mfma_f32_16x16x32_bf16 v[32:35], v[146:149], v[198:201], v[32:35]
	v_mfma_f32_16x16x32_bf16 v[24:27], v[154:157], v[198:201], v[24:27]
	v_mfma_f32_16x16x32_bf16 v[16:19], v[146:149], v[206:209], v[16:19]
	v_mfma_f32_16x16x32_bf16 v[8:11], v[154:157], v[206:209], v[8:11]
	s_setprio 0
	s_setprio 1
	v_mfma_f32_16x16x32_bf16 v[60:63], v[158:161], v[178:181], 0
	v_mfma_f32_16x16x32_bf16 v[52:55], v[166:169], v[178:181], 0
	v_mfma_f32_16x16x32_bf16 v[44:47], v[158:161], v[186:189], 0
	v_mfma_f32_16x16x32_bf16 v[36:39], v[166:169], v[186:189], 0
	v_mfma_f32_16x16x32_bf16 v[28:31], v[158:161], v[194:197], 0
	v_mfma_f32_16x16x32_bf16 v[20:23], v[166:169], v[194:197], 0
	v_mfma_f32_16x16x32_bf16 v[12:15], v[158:161], v[202:205], 0
	v_mfma_f32_16x16x32_bf16 v[4:7], v[166:169], v[202:205], 0
	v_mfma_f32_16x16x32_bf16 v[60:63], v[162:165], v[182:185], v[60:63]
	v_mfma_f32_16x16x32_bf16 v[52:55], v[170:173], v[182:185], v[52:55]
	v_mfma_f32_16x16x32_bf16 v[44:47], v[162:165], v[190:193], v[44:47]
	v_mfma_f32_16x16x32_bf16 v[36:39], v[170:173], v[190:193], v[36:39]
	v_mfma_f32_16x16x32_bf16 v[28:31], v[162:165], v[198:201], v[28:31]
	v_mfma_f32_16x16x32_bf16 v[20:23], v[170:173], v[198:201], v[20:23]
	v_mfma_f32_16x16x32_bf16 v[12:15], v[162:165], v[206:209], v[12:15]
	v_mfma_f32_16x16x32_bf16 v[4:7], v[170:173], v[206:209], v[4:7]
	s_barrier
	s_setprio 0
	s_branch .La1_ph3
.LBB0_446:
	s_add_u32 s28, s0, 0xfffc0080
	s_addc_u32 s29, s1, -1
	s_add_i32 s52, 16, 0x10000
	s_cmp_eq_u32 s51, 12
	s_cselect_b32 s31, s3, s29
	s_cselect_b32 s30, s23, s28
	v_add_u32_e32 v3, s52, v175
	s_cselect_b32 s29, s21, s50
	s_cselect_b32 s28, s48, s49
	s_add_i32 s54, 16, 0x14000
	ds_read_b128 v[142:145], v3
	ds_read_b128 v[146:149], v3 offset:1024
	ds_read_b128 v[150:153], v3 offset:2048
	ds_read_b128 v[154:157], v3 offset:3072
	v_add_u32_e32 v3, s54, v175
	ds_read_b128 v[158:161], v3
	ds_read_b128 v[162:165], v3 offset:1024
	ds_read_b128 v[166:169], v3 offset:2048
	ds_read_b128 v[170:173], v3 offset:3072
	v_lshl_add_u64 v[210:211], s[0:1], 0, v[138:139]
	s_add_i32 m0, s39, 0xc000
	ds_read_b128 v[178:181], v177
	ds_read_b128 v[182:185], v177 offset:1024
	ds_read_b128 v[186:189], v177 offset:2048
	ds_read_b128 v[190:193], v177 offset:3072
	ds_read_b128 v[194:197], v177 offset:4096
	ds_read_b128 v[198:201], v177 offset:5120
	ds_read_b128 v[202:205], v177 offset:6144
	ds_read_b128 v[206:209], v177 offset:7168
	global_load_lds_dwordx4 v[210:211], off
	v_lshl_add_u64 v[210:211], s[0:1], 0, v[140:141]
	s_add_i32 m0, s39, 0xe000
	s_nop 0
	global_load_lds_dwordx4 v[210:211], off
	s_waitcnt vmcnt(8)
	s_waitcnt lgkmcnt(0)
	s_barrier
	s_setprio 1
	s_waitcnt lgkmcnt(0)
	v_mfma_f32_16x16x32_bf16 v[128:131], v[142:145], v[178:181], v[128:131]
	v_mfma_f32_16x16x32_bf16 v[120:123], v[150:153], v[178:181], v[120:123]
	v_mfma_f32_16x16x32_bf16 v[112:115], v[142:145], v[186:189], v[112:115]
	v_mfma_f32_16x16x32_bf16 v[104:107], v[150:153], v[186:189], v[104:107]
	v_mfma_f32_16x16x32_bf16 v[96:99], v[142:145], v[194:197], v[96:99]
	v_mfma_f32_16x16x32_bf16 v[88:91], v[150:153], v[194:197], v[88:91]
	v_mfma_f32_16x16x32_bf16 v[80:83], v[142:145], v[202:205], v[80:83]
	v_mfma_f32_16x16x32_bf16 v[72:75], v[150:153], v[202:205], v[72:75]
	v_mfma_f32_16x16x32_bf16 v[128:131], v[146:149], v[182:185], v[128:131]
	v_mfma_f32_16x16x32_bf16 v[120:123], v[154:157], v[182:185], v[120:123]
	v_mfma_f32_16x16x32_bf16 v[112:115], v[146:149], v[190:193], v[112:115]
	v_mfma_f32_16x16x32_bf16 v[104:107], v[154:157], v[190:193], v[104:107]
	v_mfma_f32_16x16x32_bf16 v[96:99], v[146:149], v[198:201], v[96:99]
	v_mfma_f32_16x16x32_bf16 v[88:91], v[154:157], v[198:201], v[88:91]
	v_mfma_f32_16x16x32_bf16 v[80:83], v[146:149], v[206:209], v[80:83]
	v_mfma_f32_16x16x32_bf16 v[72:75], v[154:157], v[206:209], v[72:75]
	s_setprio 0
	s_setprio 1
	v_mfma_f32_16x16x32_bf16 v[124:127], v[158:161], v[178:181], v[124:127]
	v_mfma_f32_16x16x32_bf16 v[116:119], v[166:169], v[178:181], v[116:119]
	v_mfma_f32_16x16x32_bf16 v[108:111], v[158:161], v[186:189], v[108:111]
	v_mfma_f32_16x16x32_bf16 v[100:103], v[166:169], v[186:189], v[100:103]
	v_mfma_f32_16x16x32_bf16 v[92:95], v[158:161], v[194:197], v[92:95]
	v_mfma_f32_16x16x32_bf16 v[84:87], v[166:169], v[194:197], v[84:87]
	v_mfma_f32_16x16x32_bf16 v[76:79], v[158:161], v[202:205], v[76:79]
	v_mfma_f32_16x16x32_bf16 v[68:71], v[166:169], v[202:205], v[68:71]
	v_mfma_f32_16x16x32_bf16 v[124:127], v[162:165], v[182:185], v[124:127]
	v_mfma_f32_16x16x32_bf16 v[116:119], v[170:173], v[182:185], v[116:119]
	v_mfma_f32_16x16x32_bf16 v[108:111], v[162:165], v[190:193], v[108:111]
	v_mfma_f32_16x16x32_bf16 v[100:103], v[170:173], v[190:193], v[100:103]
	v_mfma_f32_16x16x32_bf16 v[92:95], v[162:165], v[198:201], v[92:95]
	v_mfma_f32_16x16x32_bf16 v[84:87], v[170:173], v[198:201], v[84:87]
	v_mfma_f32_16x16x32_bf16 v[76:79], v[162:165], v[206:209], v[76:79]
	v_mfma_f32_16x16x32_bf16 v[68:71], v[170:173], v[206:209], v[68:71]
	s_barrier
	s_setprio 0
	s_add_i32 s52, s52, s38
	v_lshl_add_u64 v[210:211], s[28:29], 0, v[134:135]
	s_mov_b32 m0, s52
	ds_read_b128 v[178:181], v177 offset:16384
	ds_read_b128 v[182:185], v177 offset:17408
	ds_read_b128 v[186:189], v177 offset:18432
	ds_read_b128 v[190:193], v177 offset:19456
	ds_read_b128 v[194:197], v177 offset:20480
	ds_read_b128 v[198:201], v177 offset:21504
	ds_read_b128 v[202:205], v177 offset:22528
	ds_read_b128 v[206:209], v177 offset:23552
	global_load_lds_dwordx4 v[210:211], off
	s_add_i32 m0, s52, 0x2000
	s_add_u32 s52, s28, 0x40000
	v_lshl_add_u64 v[212:213], s[28:29], 0, v[0:1]
	s_addc_u32 s53, s29, 0
	s_add_i32 s54, s54, s38
	global_load_lds_dwordx4 v[212:213], off
	v_lshl_add_u64 v[214:215], s[52:53], 0, v[134:135]
	s_mov_b32 m0, s54
	v_lshl_add_u64 v[216:217], s[30:31], 0, v[132:133]
	global_load_lds_dwordx4 v[214:215], off
	v_lshl_add_u64 v[214:215], s[52:53], 0, v[0:1]
	s_add_i32 m0, s54, 0x2000
	s_nop 0
	global_load_lds_dwordx4 v[214:215], off
	v_lshl_add_u64 v[214:215], s[30:31], 0, v[136:137]
	s_waitcnt vmcnt(6)
	s_waitcnt lgkmcnt(0)
	s_barrier
	s_setprio 1
	s_waitcnt lgkmcnt(0)
	v_mfma_f32_16x16x32_bf16 v[64:67], v[142:145], v[178:181], v[64:67]
	v_mfma_f32_16x16x32_bf16 v[56:59], v[150:153], v[178:181], v[56:59]
	v_mfma_f32_16x16x32_bf16 v[48:51], v[142:145], v[186:189], v[48:51]
	v_mfma_f32_16x16x32_bf16 v[40:43], v[150:153], v[186:189], v[40:43]
	v_mfma_f32_16x16x32_bf16 v[32:35], v[142:145], v[194:197], v[32:35]
	v_mfma_f32_16x16x32_bf16 v[24:27], v[150:153], v[194:197], v[24:27]
	v_mfma_f32_16x16x32_bf16 v[16:19], v[142:145], v[202:205], v[16:19]
	v_mfma_f32_16x16x32_bf16 v[8:11], v[150:153], v[202:205], v[8:11]
	v_mfma_f32_16x16x32_bf16 v[64:67], v[146:149], v[182:185], v[64:67]
	v_mfma_f32_16x16x32_bf16 v[56:59], v[154:157], v[182:185], v[56:59]
	v_mfma_f32_16x16x32_bf16 v[48:51], v[146:149], v[190:193], v[48:51]
	v_mfma_f32_16x16x32_bf16 v[40:43], v[154:157], v[190:193], v[40:43]
	v_mfma_f32_16x16x32_bf16 v[32:35], v[146:149], v[198:201], v[32:35]
	v_mfma_f32_16x16x32_bf16 v[24:27], v[154:157], v[198:201], v[24:27]
	v_mfma_f32_16x16x32_bf16 v[16:19], v[146:149], v[206:209], v[16:19]
	v_mfma_f32_16x16x32_bf16 v[8:11], v[154:157], v[206:209], v[8:11]
	s_setprio 0
	s_setprio 1
	v_mfma_f32_16x16x32_bf16 v[60:63], v[158:161], v[178:181], v[60:63]
	v_mfma_f32_16x16x32_bf16 v[52:55], v[166:169], v[178:181], v[52:55]
	v_mfma_f32_16x16x32_bf16 v[44:47], v[158:161], v[186:189], v[44:47]
	v_mfma_f32_16x16x32_bf16 v[36:39], v[166:169], v[186:189], v[36:39]
	v_mfma_f32_16x16x32_bf16 v[28:31], v[158:161], v[194:197], v[28:31]
	v_mfma_f32_16x16x32_bf16 v[20:23], v[166:169], v[194:197], v[20:23]
	v_mfma_f32_16x16x32_bf16 v[12:15], v[158:161], v[202:205], v[12:15]
	v_mfma_f32_16x16x32_bf16 v[4:7], v[166:169], v[202:205], v[4:7]
	v_mfma_f32_16x16x32_bf16 v[60:63], v[162:165], v[182:185], v[60:63]
	v_mfma_f32_16x16x32_bf16 v[52:55], v[170:173], v[182:185], v[52:55]
	v_mfma_f32_16x16x32_bf16 v[44:47], v[162:165], v[190:193], v[44:47]
	v_mfma_f32_16x16x32_bf16 v[36:39], v[170:173], v[190:193], v[36:39]
	v_mfma_f32_16x16x32_bf16 v[28:31], v[162:165], v[198:201], v[28:31]
	v_mfma_f32_16x16x32_bf16 v[20:23], v[170:173], v[198:201], v[20:23]
	v_mfma_f32_16x16x32_bf16 v[12:15], v[162:165], v[206:209], v[12:15]
	v_mfma_f32_16x16x32_bf16 v[4:7], v[170:173], v[206:209], v[4:7]
	s_barrier
	s_setprio 0

.La1pf_skip:
	s_waitcnt lgkmcnt(0)
	s_barrier
	s_setprio 1
	s_waitcnt lgkmcnt(0)
	v_mfma_f32_16x16x32_bf16 v[128:131], v[142:145], v[178:181], v[128:131]
	v_mfma_f32_16x16x32_bf16 v[120:123], v[150:153], v[178:181], v[120:123]
	v_mfma_f32_16x16x32_bf16 v[112:115], v[142:145], v[186:189], v[112:115]
	v_mfma_f32_16x16x32_bf16 v[104:107], v[150:153], v[186:189], v[104:107]
	v_mfma_f32_16x16x32_bf16 v[96:99], v[142:145], v[194:197], v[96:99]
	v_mfma_f32_16x16x32_bf16 v[88:91], v[150:153], v[194:197], v[88:91]
	v_mfma_f32_16x16x32_bf16 v[80:83], v[142:145], v[202:205], v[80:83]
	v_mfma_f32_16x16x32_bf16 v[72:75], v[150:153], v[202:205], v[72:75]
	v_mfma_f32_16x16x32_bf16 v[128:131], v[146:149], v[182:185], v[128:131]
	v_mfma_f32_16x16x32_bf16 v[120:123], v[154:157], v[182:185], v[120:123]
	v_mfma_f32_16x16x32_bf16 v[112:115], v[146:149], v[190:193], v[112:115]
	v_mfma_f32_16x16x32_bf16 v[104:107], v[154:157], v[190:193], v[104:107]
	v_mfma_f32_16x16x32_bf16 v[96:99], v[146:149], v[198:201], v[96:99]
	v_mfma_f32_16x16x32_bf16 v[88:91], v[154:157], v[198:201], v[88:91]
	v_mfma_f32_16x16x32_bf16 v[80:83], v[146:149], v[206:209], v[80:83]
	v_mfma_f32_16x16x32_bf16 v[72:75], v[154:157], v[206:209], v[72:75]
	s_setprio 0
	s_setprio 1
	v_mfma_f32_16x16x32_bf16 v[124:127], v[158:161], v[178:181], v[124:127]
	v_mfma_f32_16x16x32_bf16 v[116:119], v[166:169], v[178:181], v[116:119]
	v_mfma_f32_16x16x32_bf16 v[108:111], v[158:161], v[186:189], v[108:111]
	v_mfma_f32_16x16x32_bf16 v[100:103], v[166:169], v[186:189], v[100:103]
	v_mfma_f32_16x16x32_bf16 v[92:95], v[158:161], v[194:197], v[92:95]
	v_mfma_f32_16x16x32_bf16 v[84:87], v[166:169], v[194:197], v[84:87]
	v_mfma_f32_16x16x32_bf16 v[76:79], v[158:161], v[202:205], v[76:79]
	v_mfma_f32_16x16x32_bf16 v[68:71], v[166:169], v[202:205], v[68:71]
	v_mfma_f32_16x16x32_bf16 v[124:127], v[162:165], v[182:185], v[124:127]
	v_mfma_f32_16x16x32_bf16 v[116:119], v[170:173], v[182:185], v[116:119]
	v_mfma_f32_16x16x32_bf16 v[108:111], v[162:165], v[190:193], v[108:111]
	v_mfma_f32_16x16x32_bf16 v[100:103], v[170:173], v[190:193], v[100:103]
	v_mfma_f32_16x16x32_bf16 v[92:95], v[162:165], v[198:201], v[92:95]
	v_mfma_f32_16x16x32_bf16 v[84:87], v[170:173], v[198:201], v[84:87]
	v_mfma_f32_16x16x32_bf16 v[76:79], v[162:165], v[206:209], v[76:79]
	v_mfma_f32_16x16x32_bf16 v[68:71], v[170:173], v[206:209], v[68:71]
	s_barrier
	s_setprio 0
	s_add_i32 s30, s52, s38
	v_lshl_add_u64 v[210:211], v[210:211], 0, s[84:85]
	s_mov_b32 m0, s30
	ds_read_b128 v[178:181], v177 offset:49152
	ds_read_b128 v[182:185], v177 offset:50176
	ds_read_b128 v[186:189], v177 offset:51200
	ds_read_b128 v[190:193], v177 offset:52224
	ds_read_b128 v[194:197], v177 offset:53248
	ds_read_b128 v[198:201], v177 offset:54272
	ds_read_b128 v[202:205], v177 offset:55296
	ds_read_b128 v[206:209], v177 offset:56320
	global_load_lds_dwordx4 v[210:211], off
	s_add_i32 m0, s30, 0x2000
	s_add_u32 s28, s28, 0x40080
	v_lshl_add_u64 v[210:211], v[212:213], 0, s[84:85]
	s_addc_u32 s29, s29, 0
	s_add_i32 s30, s53, s38
	global_load_lds_dwordx4 v[210:211], off
	v_lshl_add_u64 v[210:211], s[28:29], 0, v[134:135]
	s_mov_b32 m0, s30
	s_nop 0
	global_load_lds_dwordx4 v[210:211], off
	v_lshl_add_u64 v[210:211], s[28:29], 0, v[0:1]
	s_add_i32 m0, s30, 0x2000
	s_nop 0
	global_load_lds_dwordx4 v[210:211], off
	v_lshl_add_u64 v[210:211], v[214:215], 0, s[84:85]
	s_mov_b32 m0, s44
	s_nop 0
	global_load_lds_dwordx4 v[210:211], off
	v_lshl_add_u64 v[210:211], v[216:217], 0, s[84:85]
	s_mov_b32 m0, s45
	s_nop 0
	global_load_lds_dwordx4 v[210:211], off
	s_cmp_eq_u32 s51, 12
	s_cbranch_scc1 .La1w4_last
	s_waitcnt vmcnt(8)
	s_branch .La1w4_j

.La1w4_j:
	s_waitcnt lgkmcnt(0)
	s_barrier
	s_setprio 1
	s_waitcnt lgkmcnt(0)
	v_mfma_f32_16x16x32_bf16 v[64:67], v[142:145], v[178:181], v[64:67]
	v_mfma_f32_16x16x32_bf16 v[56:59], v[150:153], v[178:181], v[56:59]
	v_mfma_f32_16x16x32_bf16 v[48:51], v[142:145], v[186:189], v[48:51]
	v_mfma_f32_16x16x32_bf16 v[40:43], v[150:153], v[186:189], v[40:43]
	v_mfma_f32_16x16x32_bf16 v[32:35], v[142:145], v[194:197], v[32:35]
	v_mfma_f32_16x16x32_bf16 v[24:27], v[150:153], v[194:197], v[24:27]
	v_mfma_f32_16x16x32_bf16 v[16:19], v[142:145], v[202:205], v[16:19]
	v_mfma_f32_16x16x32_bf16 v[8:11], v[150:153], v[202:205], v[8:11]
	v_mfma_f32_16x16x32_bf16 v[64:67], v[146:149], v[182:185], v[64:67]
	v_mfma_f32_16x16x32_bf16 v[56:59], v[154:157], v[182:185], v[56:59]
	v_mfma_f32_16x16x32_bf16 v[48:51], v[146:149], v[190:193], v[48:51]
	v_mfma_f32_16x16x32_bf16 v[40:43], v[154:157], v[190:193], v[40:43]
	v_mfma_f32_16x16x32_bf16 v[32:35], v[146:149], v[198:201], v[32:35]
	v_mfma_f32_16x16x32_bf16 v[24:27], v[154:157], v[198:201], v[24:27]
	v_mfma_f32_16x16x32_bf16 v[16:19], v[146:149], v[206:209], v[16:19]
	v_mfma_f32_16x16x32_bf16 v[8:11], v[154:157], v[206:209], v[8:11]
	s_setprio 0
	s_setprio 1
	v_mfma_f32_16x16x32_bf16 v[60:63], v[158:161], v[178:181], v[60:63]
	v_mfma_f32_16x16x32_bf16 v[52:55], v[166:169], v[178:181], v[52:55]
	v_mfma_f32_16x16x32_bf16 v[44:47], v[158:161], v[186:189], v[44:47]
	v_mfma_f32_16x16x32_bf16 v[36:39], v[166:169], v[186:189], v[36:39]
	v_mfma_f32_16x16x32_bf16 v[28:31], v[158:161], v[194:197], v[28:31]
	v_mfma_f32_16x16x32_bf16 v[20:23], v[166:169], v[194:197], v[20:23]
	v_mfma_f32_16x16x32_bf16 v[12:15], v[158:161], v[202:205], v[12:15]
	v_mfma_f32_16x16x32_bf16 v[4:7], v[166:169], v[202:205], v[4:7]
	v_mfma_f32_16x16x32_bf16 v[60:63], v[162:165], v[182:185], v[60:63]
	v_mfma_f32_16x16x32_bf16 v[52:55], v[170:173], v[182:185], v[52:55]
	v_mfma_f32_16x16x32_bf16 v[44:47], v[162:165], v[190:193], v[44:47]
	v_mfma_f32_16x16x32_bf16 v[36:39], v[170:173], v[190:193], v[36:39]
	v_mfma_f32_16x16x32_bf16 v[28:31], v[162:165], v[198:201], v[28:31]
	v_mfma_f32_16x16x32_bf16 v[20:23], v[170:173], v[198:201], v[20:23]
	v_mfma_f32_16x16x32_bf16 v[12:15], v[162:165], v[206:209], v[12:15]
	v_mfma_f32_16x16x32_bf16 v[4:7], v[170:173], v[206:209], v[4:7]
	s_barrier
	s_setprio 0
	s_add_i32 s51, s51, 2
	s_add_u32 s0, s0, 0x100
	s_addc_u32 s1, s1, 0
	s_add_u32 s49, s49, 0x100
	s_addc_u32 s50, s50, 0
	s_cmp_gt_u32 s51, 13
	s_cbranch_scc0 .LBB0_446
	s_and_b64 vcc, exec, s[18:19]
	s_cbranch_vccz .LBB0_449
	s_barrier

.LBB0_620:
	s_add_i32 s58, s34, 2
	s_add_u32 s59, s22, s30
	s_addc_u32 s35, s23, s31
	s_add_u32 s60, s0, s30
	s_addc_u32 s61, s1, s31
	s_add_i32 s62, 16, 0x10000
	s_cmp_eq_u32 s54, s34
	s_cselect_b32 s35, s9, s35
	s_cselect_b32 s34, s8, s59
	v_add_u32_e32 v149, s62, v147
	s_cselect_b32 s61, s29, s61
	s_cselect_b32 s60, s28, s60
	s_add_i32 s59, 16, 0x14000
	ds_read_b128 v[150:153], v149
	ds_read_b128 v[154:157], v149 offset:1024
	ds_read_b128 v[158:161], v149 offset:2048
	ds_read_b128 v[162:165], v149 offset:3072
	v_add_u32_e32 v149, s59, v147
	ds_read_b128 v[166:169], v149
	ds_read_b128 v[170:173], v149 offset:1024
	ds_read_b128 v[174:177], v149 offset:2048
	ds_read_b128 v[178:181], v149 offset:3072
	v_lshl_add_u64 v[214:215], s[22:23], 0, v[144:145]
	s_add_i32 m0, s47, 0xc000
	ds_read_b128 v[182:185], v148
	ds_read_b128 v[186:189], v148 offset:1024
	ds_read_b128 v[190:193], v148 offset:2048
	ds_read_b128 v[194:197], v148 offset:3072
	ds_read_b128 v[198:201], v148 offset:4096
	ds_read_b128 v[202:205], v148 offset:5120
	ds_read_b128 v[206:209], v148 offset:6144
	ds_read_b128 v[210:213], v148 offset:7168
	global_load_lds_dwordx4 v[214:215], off
	v_lshl_add_u64 v[214:215], s[22:23], 0, v[142:143]
	s_add_i32 m0, s47, 0xe000
	s_nop 0
	global_load_lds_dwordx4 v[214:215], off
	s_waitcnt vmcnt(8)
	s_waitcnt lgkmcnt(0)
	s_barrier
	s_setprio 1
	s_waitcnt lgkmcnt(0)
	v_mfma_f32_16x16x32_bf16 v[128:131], v[150:153], v[182:185], v[128:131]
	v_mfma_f32_16x16x32_bf16 v[124:127], v[158:161], v[182:185], v[124:127]
	v_mfma_f32_16x16x32_bf16 v[120:123], v[150:153], v[190:193], v[120:123]
	v_mfma_f32_16x16x32_bf16 v[116:119], v[158:161], v[190:193], v[116:119]
	v_mfma_f32_16x16x32_bf16 v[112:115], v[150:153], v[198:201], v[112:115]
	v_mfma_f32_16x16x32_bf16 v[108:111], v[158:161], v[198:201], v[108:111]
	v_mfma_f32_16x16x32_bf16 v[104:107], v[150:153], v[206:209], v[104:107]
	v_mfma_f32_16x16x32_bf16 v[100:103], v[158:161], v[206:209], v[100:103]
	v_mfma_f32_16x16x32_bf16 v[128:131], v[154:157], v[186:189], v[128:131]
	v_mfma_f32_16x16x32_bf16 v[124:127], v[162:165], v[186:189], v[124:127]
	v_mfma_f32_16x16x32_bf16 v[120:123], v[154:157], v[194:197], v[120:123]
	v_mfma_f32_16x16x32_bf16 v[116:119], v[162:165], v[194:197], v[116:119]
	v_mfma_f32_16x16x32_bf16 v[112:115], v[154:157], v[202:205], v[112:115]
	v_mfma_f32_16x16x32_bf16 v[108:111], v[162:165], v[202:205], v[108:111]
	v_mfma_f32_16x16x32_bf16 v[104:107], v[154:157], v[210:213], v[104:107]
	v_mfma_f32_16x16x32_bf16 v[100:103], v[162:165], v[210:213], v[100:103]
	s_setprio 0
	s_setprio 1
	v_mfma_f32_16x16x32_bf16 v[64:67], v[166:169], v[182:185], v[64:67]
	v_mfma_f32_16x16x32_bf16 v[60:63], v[174:177], v[182:185], v[60:63]
	v_mfma_f32_16x16x32_bf16 v[56:59], v[166:169], v[190:193], v[56:59]
	v_mfma_f32_16x16x32_bf16 v[52:55], v[174:177], v[190:193], v[52:55]
	v_mfma_f32_16x16x32_bf16 v[48:51], v[166:169], v[198:201], v[48:51]
	v_mfma_f32_16x16x32_bf16 v[44:47], v[174:177], v[198:201], v[44:47]
	v_mfma_f32_16x16x32_bf16 v[40:43], v[166:169], v[206:209], v[40:43]
	v_mfma_f32_16x16x32_bf16 v[36:39], v[174:177], v[206:209], v[36:39]
	v_mfma_f32_16x16x32_bf16 v[64:67], v[170:173], v[186:189], v[64:67]
	v_mfma_f32_16x16x32_bf16 v[60:63], v[178:181], v[186:189], v[60:63]
	v_mfma_f32_16x16x32_bf16 v[56:59], v[170:173], v[194:197], v[56:59]
	v_mfma_f32_16x16x32_bf16 v[52:55], v[178:181], v[194:197], v[52:55]
	v_mfma_f32_16x16x32_bf16 v[48:51], v[170:173], v[202:205], v[48:51]
	v_mfma_f32_16x16x32_bf16 v[44:47], v[178:181], v[202:205], v[44:47]
	v_mfma_f32_16x16x32_bf16 v[40:43], v[170:173], v[210:213], v[40:43]
	v_mfma_f32_16x16x32_bf16 v[36:39], v[178:181], v[210:213], v[36:39]
	s_barrier
	s_setprio 0
	s_add_i32 s62, s62, s42
	v_lshl_add_u64 v[214:215], s[60:61], 0, v[134:135]
	s_mov_b32 m0, s62
	ds_read_b128 v[182:185], v148 offset:16384
	ds_read_b128 v[186:189], v148 offset:17408
	ds_read_b128 v[190:193], v148 offset:18432
	ds_read_b128 v[194:197], v148 offset:19456
	ds_read_b128 v[198:201], v148 offset:20480
	ds_read_b128 v[202:205], v148 offset:21504
	ds_read_b128 v[206:209], v148 offset:22528
	ds_read_b128 v[210:213], v148 offset:23552
	global_load_lds_dwordx4 v[214:215], off
	s_add_i32 m0, s62, 0x2000
	v_lshl_add_u64 v[216:217], s[60:61], 0, v[0:1]
	s_add_u32 s60, s60, s40
	s_addc_u32 s61, s61, 0
	s_add_i32 s59, s59, s42
	global_load_lds_dwordx4 v[216:217], off
	v_lshl_add_u64 v[218:219], s[60:61], 0, v[134:135]
	s_mov_b32 m0, s59
	v_lshl_add_u64 v[220:221], s[60:61], 0, v[0:1]
	global_load_lds_dwordx4 v[218:219], off
	s_add_i32 m0, s59, 0x2000
	v_lshl_add_u64 v[224:225], s[34:35], 0, v[136:137]
	global_load_lds_dwordx4 v[220:221], off
	v_lshl_add_u64 v[226:227], s[34:35], 0, v[132:133]
	s_waitcnt vmcnt(6)
	s_waitcnt lgkmcnt(0)
	s_barrier
	s_setprio 1
	s_waitcnt lgkmcnt(0)
	v_mfma_f32_16x16x32_bf16 v[96:99], v[150:153], v[182:185], v[96:99]
	v_mfma_f32_16x16x32_bf16 v[92:95], v[158:161], v[182:185], v[92:95]
	v_mfma_f32_16x16x32_bf16 v[88:91], v[150:153], v[190:193], v[88:91]
	v_mfma_f32_16x16x32_bf16 v[84:87], v[158:161], v[190:193], v[84:87]
	v_mfma_f32_16x16x32_bf16 v[80:83], v[150:153], v[198:201], v[80:83]
	v_mfma_f32_16x16x32_bf16 v[76:79], v[158:161], v[198:201], v[76:79]
	v_mfma_f32_16x16x32_bf16 v[72:75], v[150:153], v[206:209], v[72:75]
	v_mfma_f32_16x16x32_bf16 v[68:71], v[158:161], v[206:209], v[68:71]
	v_mfma_f32_16x16x32_bf16 v[96:99], v[154:157], v[186:189], v[96:99]
	v_mfma_f32_16x16x32_bf16 v[92:95], v[162:165], v[186:189], v[92:95]
	v_mfma_f32_16x16x32_bf16 v[88:91], v[154:157], v[194:197], v[88:91]
	v_mfma_f32_16x16x32_bf16 v[84:87], v[162:165], v[194:197], v[84:87]
	v_mfma_f32_16x16x32_bf16 v[80:83], v[154:157], v[202:205], v[80:83]
	v_mfma_f32_16x16x32_bf16 v[76:79], v[162:165], v[202:205], v[76:79]
	v_mfma_f32_16x16x32_bf16 v[72:75], v[154:157], v[210:213], v[72:75]
	v_mfma_f32_16x16x32_bf16 v[68:71], v[162:165], v[210:213], v[68:71]
	s_setprio 0
	s_setprio 1
	v_mfma_f32_16x16x32_bf16 v[32:35], v[166:169], v[182:185], v[32:35]
	v_mfma_f32_16x16x32_bf16 v[28:31], v[174:177], v[182:185], v[28:31]
	v_mfma_f32_16x16x32_bf16 v[24:27], v[166:169], v[190:193], v[24:27]
	v_mfma_f32_16x16x32_bf16 v[20:23], v[174:177], v[190:193], v[20:23]
	v_mfma_f32_16x16x32_bf16 v[16:19], v[166:169], v[198:201], v[16:19]
	v_mfma_f32_16x16x32_bf16 v[12:15], v[174:177], v[198:201], v[12:15]
	v_mfma_f32_16x16x32_bf16 v[8:11], v[166:169], v[206:209], v[8:11]
	v_mfma_f32_16x16x32_bf16 v[4:7], v[174:177], v[206:209], v[4:7]
	v_mfma_f32_16x16x32_bf16 v[32:35], v[170:173], v[186:189], v[32:35]
	v_mfma_f32_16x16x32_bf16 v[28:31], v[178:181], v[186:189], v[28:31]
	v_mfma_f32_16x16x32_bf16 v[24:27], v[170:173], v[194:197], v[24:27]
	v_mfma_f32_16x16x32_bf16 v[20:23], v[178:181], v[194:197], v[20:23]
	v_mfma_f32_16x16x32_bf16 v[16:19], v[170:173], v[202:205], v[16:19]
	v_mfma_f32_16x16x32_bf16 v[12:15], v[178:181], v[202:205], v[12:15]
	v_mfma_f32_16x16x32_bf16 v[8:11], v[170:173], v[210:213], v[8:11]
	v_mfma_f32_16x16x32_bf16 v[4:7], v[178:181], v[210:213], v[4:7]
	s_barrier
	s_setprio 0
	s_add_i32 s59, 16, 0x18000
	v_add_u32_e32 v149, s59, v147
	s_add_i32 s60, 16, 0x1c000
	ds_read_b128 v[150:153], v149
	ds_read_b128 v[154:157], v149 offset:1024
	ds_read_b128 v[158:161], v149 offset:2048
	ds_read_b128 v[162:165], v149 offset:3072
	v_add_u32_e32 v149, s60, v147
	ds_read_b128 v[166:169], v149
	ds_read_b128 v[170:173], v149 offset:1024
	ds_read_b128 v[174:177], v149 offset:2048
	ds_read_b128 v[178:181], v149 offset:3072
	s_mov_b32 m0, s47
	s_nop 0
	global_load_lds_dwordx4 v[224:225], off
	s_mov_b32 m0, s48
	s_nop 0
	global_load_lds_dwordx4 v[226:227], off
	s_add_u32 s34, s34, s40
	s_addc_u32 s35, s35, 0
	s_mov_b32 m0, s49
	v_lshl_add_u64 v[228:229], s[34:35], 0, v[136:137]
	ds_read_b128 v[182:185], v148 offset:32768
	ds_read_b128 v[186:189], v148 offset:33792
	ds_read_b128 v[190:193], v148 offset:34816
	ds_read_b128 v[194:197], v148 offset:35840
	ds_read_b128 v[198:201], v148 offset:36864
	ds_read_b128 v[202:205], v148 offset:37888
	ds_read_b128 v[206:209], v148 offset:38912
	ds_read_b128 v[210:213], v148 offset:39936
	global_load_lds_dwordx4 v[228:229], off
	v_lshl_add_u64 v[228:229], s[34:35], 0, v[132:133]
	s_mov_b32 m0, s50
	s_nop 0
	global_load_lds_dwordx4 v[228:229], off
	s_waitcnt vmcnt(8)
	s_waitcnt lgkmcnt(0)
	s_barrier
	s_setprio 1
	s_waitcnt lgkmcnt(0)
	v_mfma_f32_16x16x32_bf16 v[128:131], v[150:153], v[182:185], v[128:131]
	v_mfma_f32_16x16x32_bf16 v[124:127], v[158:161], v[182:185], v[124:127]
	v_mfma_f32_16x16x32_bf16 v[120:123], v[150:153], v[190:193], v[120:123]
	v_mfma_f32_16x16x32_bf16 v[116:119], v[158:161], v[190:193], v[116:119]
	v_mfma_f32_16x16x32_bf16 v[112:115], v[150:153], v[198:201], v[112:115]
	v_mfma_f32_16x16x32_bf16 v[108:111], v[158:161], v[198:201], v[108:111]
	v_mfma_f32_16x16x32_bf16 v[104:107], v[150:153], v[206:209], v[104:107]
	v_mfma_f32_16x16x32_bf16 v[100:103], v[158:161], v[206:209], v[100:103]
	v_mfma_f32_16x16x32_bf16 v[128:131], v[154:157], v[186:189], v[128:131]
	v_mfma_f32_16x16x32_bf16 v[124:127], v[162:165], v[186:189], v[124:127]
	v_mfma_f32_16x16x32_bf16 v[120:123], v[154:157], v[194:197], v[120:123]
	v_mfma_f32_16x16x32_bf16 v[116:119], v[162:165], v[194:197], v[116:119]
	v_mfma_f32_16x16x32_bf16 v[112:115], v[154:157], v[202:205], v[112:115]
	v_mfma_f32_16x16x32_bf16 v[108:111], v[162:165], v[202:205], v[108:111]
	v_mfma_f32_16x16x32_bf16 v[104:107], v[154:157], v[210:213], v[104:107]
	v_mfma_f32_16x16x32_bf16 v[100:103], v[162:165], v[210:213], v[100:103]
	s_setprio 0
	s_setprio 1
	v_mfma_f32_16x16x32_bf16 v[64:67], v[166:169], v[182:185], v[64:67]
	v_mfma_f32_16x16x32_bf16 v[60:63], v[174:177], v[182:185], v[60:63]
	v_mfma_f32_16x16x32_bf16 v[56:59], v[166:169], v[190:193], v[56:59]
	v_mfma_f32_16x16x32_bf16 v[52:55], v[174:177], v[190:193], v[52:55]
	v_mfma_f32_16x16x32_bf16 v[48:51], v[166:169], v[198:201], v[48:51]
	v_mfma_f32_16x16x32_bf16 v[44:47], v[174:177], v[198:201], v[44:47]
	v_mfma_f32_16x16x32_bf16 v[40:43], v[166:169], v[206:209], v[40:43]
	v_mfma_f32_16x16x32_bf16 v[36:39], v[174:177], v[206:209], v[36:39]
	v_mfma_f32_16x16x32_bf16 v[64:67], v[170:173], v[186:189], v[64:67]
	v_mfma_f32_16x16x32_bf16 v[60:63], v[178:181], v[186:189], v[60:63]
	v_mfma_f32_16x16x32_bf16 v[56:59], v[170:173], v[194:197], v[56:59]
	v_mfma_f32_16x16x32_bf16 v[52:55], v[178:181], v[194:197], v[52:55]
	v_mfma_f32_16x16x32_bf16 v[48:51], v[170:173], v[202:205], v[48:51]
	v_mfma_f32_16x16x32_bf16 v[44:47], v[178:181], v[202:205], v[44:47]
	v_mfma_f32_16x16x32_bf16 v[40:43], v[170:173], v[210:213], v[40:43]
	v_mfma_f32_16x16x32_bf16 v[36:39], v[178:181], v[210:213], v[36:39]
	s_barrier
	s_setprio 0
	s_add_i32 s34, s59, s42
	v_lshl_add_u64 v[214:215], v[214:215], 0, s[84:85]
	s_mov_b32 m0, s34
	ds_read_b128 v[182:185], v148 offset:49152
	ds_read_b128 v[186:189], v148 offset:50176
	ds_read_b128 v[190:193], v148 offset:51200
	ds_read_b128 v[194:197], v148 offset:52224
	ds_read_b128 v[198:201], v148 offset:53248
	ds_read_b128 v[202:205], v148 offset:54272
	ds_read_b128 v[206:209], v148 offset:55296
	ds_read_b128 v[210:213], v148 offset:56320
	global_load_lds_dwordx4 v[214:215], off
	v_lshl_add_u64 v[214:215], v[216:217], 0, s[84:85]
	s_add_i32 m0, s34, 0x2000
	s_add_i32 s34, s60, s42
	global_load_lds_dwordx4 v[214:215], off
	v_lshl_add_u64 v[214:215], v[218:219], 0, s[84:85]
	s_mov_b32 m0, s34
	s_nop 0
	global_load_lds_dwordx4 v[214:215], off
	v_lshl_add_u64 v[214:215], v[220:221], 0, s[84:85]
	s_add_i32 m0, s34, 0x2000
	s_nop 0
	global_load_lds_dwordx4 v[214:215], off
	v_lshl_add_u64 v[214:215], v[224:225], 0, s[84:85]
	s_mov_b32 m0, s52
	s_nop 0
	global_load_lds_dwordx4 v[214:215], off
	v_lshl_add_u64 v[214:215], v[226:227], 0, s[84:85]
	s_mov_b32 m0, s53
	s_nop 0
	global_load_lds_dwordx4 v[214:215], off
	s_waitcnt vmcnt(8)
	s_waitcnt lgkmcnt(0)
	s_barrier
	s_setprio 1
	s_waitcnt lgkmcnt(0)
	v_mfma_f32_16x16x32_bf16 v[96:99], v[150:153], v[182:185], v[96:99]
	v_mfma_f32_16x16x32_bf16 v[92:95], v[158:161], v[182:185], v[92:95]
	v_mfma_f32_16x16x32_bf16 v[88:91], v[150:153], v[190:193], v[88:91]
	v_mfma_f32_16x16x32_bf16 v[84:87], v[158:161], v[190:193], v[84:87]
	v_mfma_f32_16x16x32_bf16 v[80:83], v[150:153], v[198:201], v[80:83]
	v_mfma_f32_16x16x32_bf16 v[76:79], v[158:161], v[198:201], v[76:79]
	v_mfma_f32_16x16x32_bf16 v[72:75], v[150:153], v[206:209], v[72:75]
	v_mfma_f32_16x16x32_bf16 v[68:71], v[158:161], v[206:209], v[68:71]
	v_mfma_f32_16x16x32_bf16 v[96:99], v[154:157], v[186:189], v[96:99]
	v_mfma_f32_16x16x32_bf16 v[92:95], v[162:165], v[186:189], v[92:95]
	v_mfma_f32_16x16x32_bf16 v[88:91], v[154:157], v[194:197], v[88:91]
	v_mfma_f32_16x16x32_bf16 v[84:87], v[162:165], v[194:197], v[84:87]
	v_mfma_f32_16x16x32_bf16 v[80:83], v[154:157], v[202:205], v[80:83]
	v_mfma_f32_16x16x32_bf16 v[76:79], v[162:165], v[202:205], v[76:79]
	v_mfma_f32_16x16x32_bf16 v[72:75], v[154:157], v[210:213], v[72:75]
	v_mfma_f32_16x16x32_bf16 v[68:71], v[162:165], v[210:213], v[68:71]
	s_setprio 0
	s_setprio 1
	v_mfma_f32_16x16x32_bf16 v[32:35], v[166:169], v[182:185], v[32:35]
	v_mfma_f32_16x16x32_bf16 v[28:31], v[174:177], v[182:185], v[28:31]
	v_mfma_f32_16x16x32_bf16 v[24:27], v[166:169], v[190:193], v[24:27]
	v_mfma_f32_16x16x32_bf16 v[20:23], v[174:177], v[190:193], v[20:23]
	v_mfma_f32_16x16x32_bf16 v[16:19], v[166:169], v[198:201], v[16:19]
	v_mfma_f32_16x16x32_bf16 v[12:15], v[174:177], v[198:201], v[12:15]
	v_mfma_f32_16x16x32_bf16 v[8:11], v[166:169], v[206:209], v[8:11]
	v_mfma_f32_16x16x32_bf16 v[4:7], v[174:177], v[206:209], v[4:7]
	v_mfma_f32_16x16x32_bf16 v[32:35], v[170:173], v[186:189], v[32:35]
	v_mfma_f32_16x16x32_bf16 v[28:31], v[178:181], v[186:189], v[28:31]
	v_mfma_f32_16x16x32_bf16 v[24:27], v[170:173], v[194:197], v[24:27]
	v_mfma_f32_16x16x32_bf16 v[20:23], v[178:181], v[194:197], v[20:23]
	v_mfma_f32_16x16x32_bf16 v[16:19], v[170:173], v[202:205], v[16:19]
	v_mfma_f32_16x16x32_bf16 v[12:15], v[178:181], v[202:205], v[12:15]
	v_mfma_f32_16x16x32_bf16 v[8:11], v[170:173], v[210:213], v[8:11]
	v_mfma_f32_16x16x32_bf16 v[4:7], v[178:181], v[210:213], v[4:7]
	s_barrier
	s_setprio 0
	s_add_u32 s30, s30, 0x100
	s_addc_u32 s31, s31, 0
	v_lshl_add_u64 v[144:145], v[144:145], 0, s[86:87]
	v_lshl_add_u64 v[142:143], v[142:143], 0, s[86:87]
	s_cmp_ge_u32 s58, s51
	s_mov_b32 s34, s58
	s_cbranch_scc0 .LBB0_620
	s_and_b64 vcc, exec, s[26:27]
	s_cbranch_vccnz .LBB0_623
	s_and_b64 vcc, exec, s[6:7]
	s_cbranch_vccnz .LBB0_608
	s_branch .LBB0_624
